# P0: non-modulation workgroups hold their first loads back by two s_sleep 100
# speedup vs baseline: 1.0016x; 1.0004x over previous
.LBB0_14:
	s_load_dwordx2 s[38:39], s[6:7], 0x0
	s_load_dwordx2 s[40:41], s[6:7], 0x90
	s_waitcnt lgkmcnt(0)
	s_add_u32 s24, s36, 0x80000
	s_addc_u32 s25, s37, 0
	s_cmpk_gt_i32 s71, 0xbf
	s_cbranch_scc0 .Lp0hold_skip
	s_sleep 100
	s_sleep 100
